# P4/P6: the six residual-tile pieces staged in the K-loop's last load segment are waited for and read behind the exchange's first wait (K-loop exit waits vmcnt(6))
# speedup vs baseline: 1.0151x; 1.0018x over previous
.LBB0_572:
	s_waitcnt vmcnt(6)
	s_cmpk_gt_u32 s47, 0xff
	s_cbranch_scc1 .LBB0_574
	s_barrier
.LBB0_574:
	s_lshl_b32 s0, s15, 5
	s_lshl_b32 s6, s16, 8
	s_or_b32 s0, s6, s0
	s_lshl_b32 s40, s14, 8
	v_and_or_b32 v210, v150, 24, s0
	s_add_i32 s0, s40, s61
	v_or_b32_e32 v130, s0, v219
	v_ashrrev_i32_e32 v211, 31, v210
	v_ashrrev_i32_e32 v131, 31, v130
	v_lshl_add_u64 v[132:133], v[210:211], 1, s[38:39]
	v_lshlrev_b64 v[134:135], 11, v[130:131]
	v_lshl_add_u64 v[134:135], v[132:133], 0, v[134:135]
	s_barrier
	v_lshlrev_b32_e32 v234, 4, v1
	v_add_u32_e32 v234, s49, v234
	v_add_u32_e32 v235, 0x10000, v234
	ds_read_b128 v[194:197], v235 offset:0
	ds_read_b128 v[186:189], v235 offset:8192
	v_or_b32_e32 v134, 16, v130
	v_ashrrev_i32_e32 v135, 31, v134
	v_lshlrev_b64 v[134:135], 11, v[134:135]
	v_lshl_add_u64 v[134:135], v[132:133], 0, v[134:135]
	ds_read_b128 v[182:185], v235 offset:16384
	ds_read_b128 v[178:181], v235 offset:24576
	v_or_b32_e32 v134, 32, v130
	v_ashrrev_i32_e32 v135, 31, v134
	v_lshlrev_b64 v[134:135], 11, v[134:135]
	v_lshl_add_u64 v[134:135], v[132:133], 0, v[134:135]
	ds_read_b128 v[174:177], v234 offset:0
	ds_read_b128 v[170:173], v234 offset:8192
	v_or_b32_e32 v134, 48, v130
	v_ashrrev_i32_e32 v135, 31, v134
	v_lshlrev_b64 v[134:135], 11, v[134:135]
	v_lshl_add_u64 v[134:135], v[132:133], 0, v[134:135]
	ds_read_b128 v[166:169], v234 offset:16384
	ds_read_b128 v[162:165], v234 offset:24576
	v_add_u32_e32 v134, 0x80, v130
	v_ashrrev_i32_e32 v135, 31, v134
	v_lshlrev_b64 v[134:135], 11, v[134:135]
	v_lshl_add_u64 v[134:135], v[132:133], 0, v[134:135]
	v_add_u32_e32 v134, 0x90, v130
	v_ashrrev_i32_e32 v135, 31, v134
	v_lshlrev_b64 v[134:135], 11, v[134:135]
	v_lshl_add_u64 v[134:135], v[132:133], 0, v[134:135]
	v_add_u32_e32 v134, 0xa0, v130
	v_add_u32_e32 v130, 0xb0, v130
	v_ashrrev_i32_e32 v135, 31, v134
	v_ashrrev_i32_e32 v131, 31, v130
	v_lshlrev_b64 v[134:135], 11, v[134:135]
	v_lshlrev_b64 v[130:131], 11, v[130:131]
	v_lshl_add_u64 v[134:135], v[132:133], 0, v[134:135]
	v_lshl_add_u64 v[130:131], v[132:133], 0, v[130:131]
	s_nop 0
	global_load_dwordx4 v[134:137], v[130:131], off
	s_nop 0
	global_load_dwordx4 v[130:133], v[130:131], off offset:256
	s_waitcnt lgkmcnt(0)
	s_barrier
	v_mbcnt_lo_u32_b32 v190, -1, 0
	v_mbcnt_hi_u32_b32 v190, -1, v190
	v_and_b32_e32 v192, 64, v190
	v_xor_b32_e32 v191, 16, v190
	v_add_u32_e32 v192, 64, v192
	v_cmp_lt_i32_e32 vcc, v191, v192
	v_mul_f32_e32 v193, v129, v129
	v_fmac_f32_e32 v193, v128, v128
	v_cndmask_b32_e32 v191, v190, v191, vcc
	v_lshlrev_b32_e32 v220, 2, v191
	v_mul_f32_e32 v191, v127, v127
	v_fmac_f32_e32 v191, v126, v126
	v_add_f32_e32 v191, v191, v193
	v_mul_f32_e32 v193, v123, v123
	v_mul_f32_e32 v198, v125, v125
	v_fmac_f32_e32 v193, v122, v122
	v_fmac_f32_e32 v198, v124, v124
	v_add_f32_e32 v193, v193, v198
	v_add_f32_e32 v191, v193, v191
	v_mul_f32_e32 v193, v119, v119
	v_mul_f32_e32 v198, v121, v121
	v_fmac_f32_e32 v193, v118, v118
	v_fmac_f32_e32 v198, v120, v120
	v_add_f32_e32 v193, v193, v198
	v_add_f32_e32 v191, v193, v191
	v_mul_f32_e32 v193, v115, v115
	v_mul_f32_e32 v198, v117, v117
	v_fmac_f32_e32 v193, v114, v114
	v_fmac_f32_e32 v198, v116, v116
	v_add_f32_e32 v193, v193, v198
	v_add_f32_e32 v191, v193, v191
	v_mov_b32_e32 v193, v191
	s_nop 1
	v_permlane16_swap_b32_e32 v191, v193
	v_xor_b32_e32 v198, 32, v190
	v_cmp_lt_i32_e32 vcc, v198, v192
	s_lshl_b32 s0, s15, 2
	v_cmp_gt_u32_e64 s[6:7], 16, v1
	v_cndmask_b32_e32 v190, v190, v198, vcc
	v_lshlrev_b32_e32 v221, 2, v190
	s_waitcnt lgkmcnt(0)
	v_add_f32_e32 v190, v191, v193
	v_mov_b32_e32 v191, v190
	s_nop 1
	v_permlane32_swap_b32_e32 v190, v191
	s_add_i32 s15, s0, 0
	s_and_saveexec_b64 s[8:9], s[6:7]
	s_cbranch_execz .LBB0_576
	s_lshl_b32 s0, s1, 10
	s_add_i32 s0, s15, s0
	v_lshl_add_u32 v192, v219, 4, s0
	s_waitcnt lgkmcnt(0)
	v_add_f32_e32 v190, v190, v191
	ds_write_b32 v192, v190

.LBB0_592:
	s_or_b64 exec, exec, s[10:11]
	s_waitcnt vmcnt(0)
	ds_read_b128 v[158:161], v235 offset:32768
	ds_read_b128 v[154:157], v235 offset:40960
	ds_read_b128 v[150:153], v235 offset:49152
	ds_read_b128 v[146:149], v235 offset:57344
	ds_read_b128 v[142:145], v234 offset:32768
	ds_read_b128 v[138:141], v234 offset:40960
	s_add_u32 s0, s34, 0x10000
	s_addc_u32 s17, s35, 0
	v_cmp_eq_u32_e64 s[10:11], 0, v1
	s_and_saveexec_b64 s[18:19], s[10:11]
	s_cbranch_execz .LBB0_595
	s_mov_b64 s[20:21], exec
	v_mbcnt_lo_u32_b32 v190, s20, 0
	v_mbcnt_hi_u32_b32 v190, s21, v190
	v_cmp_eq_u32_e32 vcc, 0, v190
	s_and_b64 s[26:27], exec, vcc
	s_mov_b64 exec, s[26:27]
	s_cbranch_execz .LBB0_595
	s_lshl_b32 s26, s14, 6
	s_ashr_i32 s27, s26, 31
	s_lshl_b64 s[26:27], s[26:27], 2
	s_add_u32 s26, s0, s26
	s_addc_u32 s27, s17, s27
	s_bcnt1_i32_b64 s20, s[20:21]
	v_mov_b32_e32 v190, 0
	s_waitcnt lgkmcnt(0)
	v_mov_b32_e32 v191, s20
	global_atomic_add v190, v191, s[26:27]

.LBB0_879:
	s_waitcnt vmcnt(6)
	s_cmpk_gt_u32 s33, 0xff
	s_cbranch_scc1 .LBB0_881
	s_barrier
.LBB0_881:
	v_lshrrev_b32_e32 v214, 4, v1
	s_lshl_b32 s6, s10, 8
	s_lshl_b32 s2, s29, 8
	s_lshl_b32 s18, s31, 5
	v_lshl_or_b32 v130, v214, 3, s6
	s_add_i32 s4, s2, s30
	v_or_b32_e32 v178, s18, v130
	v_or_b32_e32 v130, s4, v213
	v_ashrrev_i32_e32 v179, 31, v178
	v_ashrrev_i32_e32 v131, 31, v130
	v_lshl_add_u64 v[132:133], v[178:179], 1, s[22:23]
	v_lshlrev_b64 v[134:135], 11, v[130:131]
	v_lshl_add_u64 v[134:135], v[132:133], 0, v[134:135]
	s_barrier
	v_lshlrev_b32_e32 v234, 4, v1
	v_add_u32_e32 v234, s36, v234
	v_add_u32_e32 v235, 0x10000, v234
	ds_read_b128 v[206:209], v235 offset:0
	ds_read_b128 v[202:205], v235 offset:8192
	v_or_b32_e32 v134, 16, v130
	v_ashrrev_i32_e32 v135, 31, v134
	v_lshlrev_b64 v[134:135], 11, v[134:135]
	v_lshl_add_u64 v[134:135], v[132:133], 0, v[134:135]
	ds_read_b128 v[198:201], v235 offset:16384
	ds_read_b128 v[186:189], v235 offset:24576
	v_or_b32_e32 v134, 32, v130
	v_ashrrev_i32_e32 v135, 31, v134
	v_lshlrev_b64 v[134:135], 11, v[134:135]
	v_lshl_add_u64 v[134:135], v[132:133], 0, v[134:135]
	ds_read_b128 v[174:177], v234 offset:0
	ds_read_b128 v[170:173], v234 offset:8192
	v_or_b32_e32 v134, 48, v130
	v_ashrrev_i32_e32 v135, 31, v134
	v_lshlrev_b64 v[134:135], 11, v[134:135]
	v_lshl_add_u64 v[134:135], v[132:133], 0, v[134:135]
	ds_read_b128 v[166:169], v234 offset:16384
	ds_read_b128 v[162:165], v234 offset:24576
	v_add_u32_e32 v134, 0x80, v130
	v_ashrrev_i32_e32 v135, 31, v134
	v_lshlrev_b64 v[134:135], 11, v[134:135]
	v_lshl_add_u64 v[134:135], v[132:133], 0, v[134:135]
	v_add_u32_e32 v134, 0x90, v130
	v_ashrrev_i32_e32 v135, 31, v134
	v_lshlrev_b64 v[134:135], 11, v[134:135]
	v_lshl_add_u64 v[134:135], v[132:133], 0, v[134:135]
	v_add_u32_e32 v134, 0xa0, v130
	v_add_u32_e32 v130, 0xb0, v130
	v_ashrrev_i32_e32 v135, 31, v134
	v_ashrrev_i32_e32 v131, 31, v130
	v_lshlrev_b64 v[134:135], 11, v[134:135]
	v_lshlrev_b64 v[130:131], 11, v[130:131]
	v_lshl_add_u64 v[134:135], v[132:133], 0, v[134:135]
	v_lshl_add_u64 v[130:131], v[132:133], 0, v[130:131]
	s_nop 0
	global_load_dwordx4 v[134:137], v[130:131], off
	s_nop 0
	global_load_dwordx4 v[130:133], v[130:131], off offset:256
	s_waitcnt lgkmcnt(0)
	s_barrier
	v_mul_f32_e32 v183, v127, v127
	v_mul_f32_e32 v184, v129, v129
	v_fmac_f32_e32 v183, v126, v126
	v_fmac_f32_e32 v184, v128, v128
	v_add_f32_e32 v183, v183, v184
	v_mul_f32_e32 v184, v123, v123
	v_mul_f32_e32 v185, v125, v125
	v_fmac_f32_e32 v184, v122, v122
	v_fmac_f32_e32 v185, v124, v124
	v_add_f32_e32 v184, v184, v185
	v_mbcnt_lo_u32_b32 v180, -1, 0
	v_add_f32_e32 v183, v184, v183
	v_mul_f32_e32 v184, v119, v119
	v_mul_f32_e32 v185, v121, v121
	v_mbcnt_hi_u32_b32 v181, -1, v180
	v_fmac_f32_e32 v184, v118, v118
	v_fmac_f32_e32 v185, v120, v120
	v_and_b32_e32 v182, 64, v181
	v_add_f32_e32 v184, v184, v185
	v_xor_b32_e32 v180, 16, v181
	v_add_u32_e32 v182, 64, v182
	v_add_f32_e32 v183, v184, v183
	v_mul_f32_e32 v184, v115, v115
	v_mul_f32_e32 v185, v117, v117
	v_cmp_lt_i32_e32 vcc, v180, v182
	v_fmac_f32_e32 v184, v114, v114
	v_fmac_f32_e32 v185, v116, v116
	v_cndmask_b32_e32 v180, v181, v180, vcc
	v_add_f32_e32 v184, v184, v185
	v_lshlrev_b32_e32 v180, 2, v180
	v_add_f32_e32 v183, v184, v183
	v_mov_b32_e32 v184, v183
	s_nop 1
	v_permlane16_swap_b32_e32 v183, v184
	v_xor_b32_e32 v185, 32, v181
	v_cmp_lt_i32_e32 vcc, v185, v182
	s_lshl_b32 s0, s31, 2
	s_add_i32 s3, s0, 0
	v_cndmask_b32_e32 v181, v181, v185, vcc
	v_lshlrev_b32_e32 v181, 2, v181
	s_waitcnt lgkmcnt(0)
	v_add_f32_e32 v182, v183, v184
	v_mov_b32_e32 v183, v182
	s_nop 1
	v_permlane32_swap_b32_e32 v182, v183
	v_cmp_gt_u32_e32 vcc, 16, v1
	s_and_saveexec_b64 s[0:1], vcc
	s_cbranch_execz .LBB0_883
	s_lshl_b32 s5, s11, 10
	s_add_i32 s5, s3, s5
	v_lshl_add_u32 v184, v213, 4, s5
	s_waitcnt lgkmcnt(0)
	v_add_f32_e32 v182, v182, v183
	ds_write_b32 v184, v182

.LBB0_899:
	s_or_b64 exec, exec, s[2:3]
	s_waitcnt vmcnt(0)
	ds_read_b128 v[158:161], v235 offset:32768
	ds_read_b128 v[154:157], v235 offset:40960
	ds_read_b128 v[150:153], v235 offset:49152
	ds_read_b128 v[146:149], v235 offset:57344
	ds_read_b128 v[142:145], v234 offset:32768
	ds_read_b128 v[138:141], v234 offset:40960
	s_add_u32 s5, s34, 0x20000
	s_addc_u32 s7, s35, 0
	v_cmp_eq_u32_e64 s[2:3], 0, v1
	s_and_saveexec_b64 s[10:11], s[2:3]
	s_cbranch_execz .LBB0_902
	s_mov_b64 s[12:13], exec
	v_mbcnt_lo_u32_b32 v182, s12, 0
	v_mbcnt_hi_u32_b32 v182, s13, v182
	v_cmp_eq_u32_e32 vcc, 0, v182
	s_and_b64 s[14:15], exec, vcc
	s_mov_b64 exec, s[14:15]
	s_cbranch_execz .LBB0_902
	s_lshl_b32 s14, s29, 6
	s_ashr_i32 s15, s14, 31
	s_lshl_b64 s[14:15], s[14:15], 2
	s_add_u32 s14, s5, s14
	s_addc_u32 s15, s7, s15
	s_bcnt1_i32_b64 s12, s[12:13]
	v_mov_b32_e32 v182, 0
	v_mov_b32_e32 v183, s12
	global_atomic_add v182, v183, s[14:15]
